# grid barrier: non-leader workgroups poll the top-level generation word directly instead of the per-XCD generation (one hop less on release)
# speedup vs baseline: 1.0145x; 1.0145x over previous
.LBB0_314:
	v_readlane_b32 s4, v253, 36
	v_readlane_b32 s5, v253, 37
	v_cvt_f32_u32_e32 v0, v3
	v_sub_u32_e32 v5, 0, v3
	v_rcp_iflag_f32_e32 v0, v0
	s_nop 1
	global_atomic_add v4, v1, v181, s[4:5] sc0
	v_mul_f32_e32 v0, 0x4f7ffffe, v0
	v_cvt_u32_f32_e32 v0, v0
	v_mul_lo_u32 v5, v5, v0
	v_mul_hi_u32 v5, v0, v5
	v_add_u32_e32 v0, v0, v5
	s_waitcnt vmcnt(0)
	v_mul_hi_u32 v0, v4, v0
	v_mul_lo_u32 v5, v0, v3
	v_sub_u32_e32 v5, v4, v5
	v_add_u32_e32 v6, 1, v0
	v_cmp_ge_u32_e32 vcc, v5, v3
	v_add_u32_e32 v4, 1, v4
	s_nop 0
	v_cndmask_b32_e32 v0, v0, v6, vcc
	v_sub_u32_e32 v6, v5, v3
	v_cndmask_b32_e32 v5, v5, v6, vcc
	v_add_u32_e32 v6, 1, v0
	v_cmp_ge_u32_e32 vcc, v5, v3
	s_nop 1
	v_cndmask_b32_e32 v0, v0, v6, vcc
	v_mul_lo_u32 v5, v3, v0
	v_add_u32_e32 v3, v5, v3
	v_cmp_ne_u32_e32 vcc, v4, v3
	s_and_saveexec_b64 s[4:5], vcc
	s_xor_b64 s[8:9], exec, s[4:5]
	s_cbranch_execz .LBB0_328
	s_add_u32 s4, s62, 0x7500
	s_addc_u32 s5, s63, 0
	s_waitcnt lgkmcnt(0)
	s_nop 3
	global_load_dword v2, v1, s[4:5] sc1
	s_waitcnt vmcnt(0)
	v_cmp_eq_u32_e32 vcc, v2, v0
	s_and_saveexec_b64 s[10:11], vcc
	s_cbranch_execz .LBB0_327
	s_mov_b32 s4, 1
	s_mov_b64 s[12:13], 0
	s_branch .LBB0_318

.LBB0_320:
	s_add_u32 s16, s62, 0x7500
	s_addc_u32 s17, s63, 0
	s_add_i32 s4, s4, 1
	s_mov_b64 s[38:39], -1
	s_nop 2
	global_load_dword v2, v1, s[16:17] sc1
	s_waitcnt vmcnt(0)
	v_cmp_ne_u32_e32 vcc, v2, v0
	s_orn2_b64 s[16:17], vcc, exec
	s_branch .LBB0_317

.LBB0_1154:
	v_readlane_b32 s4, v253, 36
	v_readlane_b32 s5, v253, 37
	v_cvt_f32_u32_e32 v0, v3
	v_sub_u32_e32 v5, 0, v3
	v_rcp_iflag_f32_e32 v0, v0
	s_nop 1
	global_atomic_add v4, v1, v181, s[4:5] sc0
	v_mul_f32_e32 v0, 0x4f7ffffe, v0
	v_cvt_u32_f32_e32 v0, v0
	v_mul_lo_u32 v5, v5, v0
	v_mul_hi_u32 v5, v0, v5
	v_add_u32_e32 v0, v0, v5
	s_waitcnt vmcnt(0)
	v_mul_hi_u32 v0, v4, v0
	v_mul_lo_u32 v5, v0, v3
	v_sub_u32_e32 v5, v4, v5
	v_add_u32_e32 v6, 1, v0
	v_cmp_ge_u32_e32 vcc, v5, v3
	v_add_u32_e32 v4, 1, v4
	s_nop 0
	v_cndmask_b32_e32 v0, v0, v6, vcc
	v_sub_u32_e32 v6, v5, v3
	v_cndmask_b32_e32 v5, v5, v6, vcc
	v_add_u32_e32 v6, 1, v0
	v_cmp_ge_u32_e32 vcc, v5, v3
	s_nop 1
	v_cndmask_b32_e32 v0, v0, v6, vcc
	v_mul_lo_u32 v5, v3, v0
	v_add_u32_e32 v3, v5, v3
	v_cmp_ne_u32_e32 vcc, v4, v3
	s_and_saveexec_b64 s[4:5], vcc
	s_xor_b64 s[8:9], exec, s[4:5]
	s_cbranch_execz .LBB0_1168
	s_add_u32 s4, s62, 0x7500
	s_addc_u32 s5, s63, 0
	s_waitcnt lgkmcnt(0)
	s_nop 3
	global_load_dword v2, v1, s[4:5] sc1
	s_waitcnt vmcnt(0)
	v_cmp_eq_u32_e32 vcc, v2, v0
	s_and_saveexec_b64 s[10:11], vcc
	s_cbranch_execz .LBB0_1167
	s_mov_b32 s1, 1
	s_mov_b64 s[12:13], 0
	s_branch .LBB0_1158

.LBB0_1160:
	s_add_u32 s4, s62, 0x7500
	s_addc_u32 s5, s63, 0
	s_add_i32 s1, s1, 1
	s_mov_b64 s[36:37], -1
	s_nop 2
	global_load_dword v2, v1, s[4:5] sc1
	s_waitcnt vmcnt(0)
	v_cmp_ne_u32_e32 vcc, v2, v0
	s_orn2_b64 s[16:17], vcc, exec
	s_branch .LBB0_1157
